# dil_tile<1> score section: the 10 second-half K fragment loads hoisted next to the first 12 (one wait instead of ten)
# baseline (speedup 1.0000x reference)
.LBB0_178:
	v_or_b32_e32 v2, s47, v147
	v_ashrrev_i32_e32 v3, 31, v2
	v_lshlrev_b64 v[4:5], 8, v[2:3]
	v_lshl_add_u64 v[12:13], v[4:5], 0, s[14:15]
	v_add_u32_e32 v15, v2, v82
	v_lshlrev_b64 v[4:5], 7, v[12:13]
	v_subrev_u32_e32 v3, s44, v15
	v_lshl_add_u64 v[10:11], s[40:41], 0, v[4:5]
	v_add_u32_e32 v18, s9, v3
	v_lshlrev_b32_e32 v8, 1, v134
	v_mov_b32_e32 v9, v1
	v_lshl_add_u64 v[4:5], v[40:41], 1, v[10:11]
	v_ashrrev_i32_e32 v19, 31, v18
	v_lshl_add_u64 v[4:5], v[4:5], 0, v[8:9]
	v_lshlrev_b64 v[18:19], 11, v[18:19]
	v_add_co_u32_e32 v4, vcc, s8, v4
	v_lshl_add_u64 v[6:7], v[42:43], 1, v[10:11]
	v_lshl_add_u64 v[18:19], s[50:51], 0, v[18:19]
	v_addc_co_u32_e32 v5, vcc, 0, v5, vcc
	v_lshl_add_u64 v[6:7], v[6:7], 0, v[8:9]
	v_lshlrev_b32_e32 v16, 1, v136
	v_mov_b32_e32 v17, v1
	v_lshl_add_u64 v[18:19], s[12:13], 1, v[18:19]
	v_lshl_add_u32 v14, v3, 2, 0
	v_or_b32_e32 v12, s46, v12
	v_add_co_u32_e32 v6, vcc, s8, v6
	v_lshl_add_u64 v[56:57], v[18:19], 0, v[16:17]
	v_add_u32_e32 v16, 0x11000, v14
	v_lshlrev_b64 v[12:13], 7, v[12:13]
	v_lshl_add_u64 v[20:21], v[10:11], 0, v[0:1]
	v_lshl_add_u64 v[22:23], v[26:27], 1, v[10:11]
	v_lshl_add_u64 v[24:25], v[28:29], 1, v[10:11]
	v_lshl_add_u64 v[60:61], v[30:31], 1, v[10:11]
	v_lshl_add_u64 v[62:63], v[32:33], 1, v[10:11]
	v_lshl_add_u64 v[64:65], v[34:35], 1, v[10:11]
	v_lshl_add_u64 v[66:67], v[36:37], 1, v[10:11]
	v_lshl_add_u64 v[68:69], v[38:39], 1, v[10:11]
	v_addc_co_u32_e32 v7, vcc, 0, v7, vcc
	ds_read_b32 v58, v16
	v_lshl_add_u64 v[16:17], v[144:145], 0, v[12:13]
	v_lshl_add_u64 v[104:105], v[20:21], 0, v[8:9]
	v_lshl_add_u64 v[106:107], v[22:23], 0, v[8:9]
	v_lshl_add_u64 v[24:25], v[24:25], 0, v[8:9]
	v_lshl_add_u64 v[108:109], v[60:61], 0, v[8:9]
	v_lshl_add_u64 v[110:111], v[62:63], 0, v[8:9]
	v_lshl_add_u64 v[112:113], v[64:65], 0, v[8:9]
	v_lshl_add_u64 v[114:115], v[66:67], 0, v[8:9]
	v_lshl_add_u64 v[116:117], v[68:69], 0, v[8:9]
	flat_load_dwordx4 v[10:13], v[16:17]
	s_nop 0
	flat_load_dwordx4 v[16:19], v[16:17] offset:64
	v_add_co_u32_e32 v54, vcc, s49, v56
	flat_load_dwordx4 v[20:23], v[104:105]
	flat_load_dwordx4 v[64:67], v[24:25]
	flat_load_dwordx4 v[60:63], v[106:107]
	flat_load_dwordx4 v[68:71], v[108:109]
	flat_load_dwordx4 v[72:75], v[110:111]
	flat_load_dwordx4 v[84:87], v[112:113]
	flat_load_dwordx4 v[88:91], v[114:115]
	flat_load_dwordx4 v[92:95], v[116:117]
	flat_load_dwordx4 v[96:99], v[4:5]
	flat_load_dwordx4 v[100:103], v[6:7] offset:512
	v_addc_co_u32_e32 v55, vcc, 0, v57, vcc
	v_readlane_b32 vcc_lo, v253, 37
	v_readlane_b32 vcc_hi, v253, 38
	s_mov_b32 s47, 0xff800000
	v_add_u32_e32 v14, 0x11400, v14
	v_lshlrev_b32_e32 v2, 8, v2
	global_load_dwordx4 v[148:151], v[104:105], off offset:64
	global_load_dwordx4 v[152:155], v[106:107], off offset:64
	global_load_dwordx4 v[156:159], v[24:25], off offset:64
	global_load_dwordx4 v[160:163], v[108:109], off offset:64
	global_load_dwordx4 v[164:167], v[110:111], off offset:64
	global_load_dwordx4 v[168:171], v[112:113], off offset:64
	global_load_dwordx4 v[172:175], v[114:115], off offset:64
	global_load_dwordx4 v[176:179], v[116:117], off offset:64
	global_load_dwordx4 v[180:183], v[4:5], off offset:64
	global_load_dwordx4 v[184:187], v[6:7], off offset:576
	s_waitcnt vmcnt(0) lgkmcnt(0)
	v_mfma_f32_16x16x32_bf16 v[20:23], v[20:23], v[10:13], 0
	v_mfma_f32_16x16x32_bf16 v[60:63], v[60:63], v[10:13], 0
	v_mfma_f32_16x16x32_bf16 v[64:67], v[64:67], v[10:13], 0
	v_mfma_f32_16x16x32_bf16 v[68:71], v[68:71], v[10:13], 0
	v_mfma_f32_16x16x32_bf16 v[72:75], v[72:75], v[10:13], 0
	v_mfma_f32_16x16x32_bf16 v[84:87], v[84:87], v[10:13], 0
	v_mfma_f32_16x16x32_bf16 v[88:91], v[88:91], v[10:13], 0
	v_mfma_f32_16x16x32_bf16 v[92:95], v[92:95], v[10:13], 0
	v_mfma_f32_16x16x32_bf16 v[96:99], v[96:99], v[10:13], 0
	v_mfma_f32_16x16x32_bf16 v[8:11], v[100:103], v[10:13], 0
	ds_read_b32 v106, v14
	v_mfma_f32_16x16x32_bf16 v[20:23], v[148:151], v[16:19], v[20:23]
	v_mfma_f32_16x16x32_bf16 v[60:63], v[152:155], v[16:19], v[60:63]
	v_mfma_f32_16x16x32_bf16 v[64:67], v[156:159], v[16:19], v[64:67]
	v_mfma_f32_16x16x32_bf16 v[68:71], v[160:163], v[16:19], v[68:71]
	v_mfma_f32_16x16x32_bf16 v[72:75], v[164:167], v[16:19], v[72:75]
	v_mfma_f32_16x16x32_bf16 v[84:87], v[168:171], v[16:19], v[84:87]
	v_mfma_f32_16x16x32_bf16 v[88:91], v[172:175], v[16:19], v[88:91]
	v_mfma_f32_16x16x32_bf16 v[92:95], v[176:179], v[16:19], v[92:95]
	v_mfma_f32_16x16x32_bf16 v[4:7], v[184:187], v[16:19], v[8:11]
	v_mfma_f32_16x16x32_bf16 v[96:99], v[180:183], v[16:19], v[96:99]
	s_nop 7
	v_max_f32_e32 v12, v58, v58
	v_cndmask_b32_e64 v13, v227, v60, s[34:35]
	v_cndmask_b32_e64 v24, v227, v69, s[66:67]
	v_cndmask_b32_e64 v25, v227, v70, s[68:69]
	v_cndmask_b32_e64 v69, v227, v72, s[72:73]
	v_cndmask_b32_e64 v83, v227, v73, s[74:75]
	v_cndmask_b32_e64 v74, v227, v74, s[76:77]
	v_cndmask_b32_e64 v75, v227, v75, s[78:79]
	v_cndmask_b32_e64 v84, v227, v84, s[80:81]
	v_cndmask_b32_e64 v85, v227, v85, s[82:83]
	v_cndmask_b32_e32 v8, v227, v20, vcc
	v_cndmask_b32_e64 v9, v227, v21, s[26:27]
	v_cndmask_b32_e64 v10, v227, v22, s[28:29]
	v_cndmask_b32_e64 v11, v227, v23, s[30:31]
	v_max3_f32 v60, v8, s47, v9
	v_cndmask_b32_e64 v16, v227, v61, s[36:37]
	v_max3_f32 v60, v60, v10, v11
	v_cndmask_b32_e64 v17, v227, v62, s[0:1]
	v_cndmask_b32_e64 v18, v227, v63, s[54:55]
	v_max3_f32 v60, v60, v13, v16
	v_cndmask_b32_e64 v19, v227, v64, s[56:57]
	v_cndmask_b32_e64 v20, v227, v65, s[58:59]
	v_max3_f32 v60, v60, v17, v18
	v_cndmask_b32_e64 v21, v227, v66, s[60:61]
	v_cndmask_b32_e64 v22, v227, v67, s[62:63]
	v_max3_f32 v60, v60, v19, v20
	v_cndmask_b32_e64 v23, v227, v68, s[64:65]
	v_max3_f32 v60, v60, v21, v22
	v_cndmask_b32_e64 v68, v227, v71, s[70:71]
	v_max3_f32 v60, v60, v23, v24
	v_max3_f32 v60, v60, v25, v68
	v_max3_f32 v60, v60, v69, v83
	v_max3_f32 v60, v60, v74, v75
	v_cndmask_b32_e64 v86, v227, v86, s[84:85]
	v_cndmask_b32_e64 v87, v227, v87, s[86:87]
	v_max3_f32 v60, v60, v84, v85
	v_cndmask_b32_e64 v88, v227, v88, s[88:89]
	v_cndmask_b32_e64 v89, v227, v89, s[90:91]
	v_max3_f32 v60, v60, v86, v87
	v_cndmask_b32_e64 v90, v227, v90, s[92:93]
	v_cndmask_b32_e64 v91, v227, v91, s[94:95]
	v_max3_f32 v60, v60, v88, v89
	v_cndmask_b32_e64 v92, v227, v92, s[96:97]
	v_cndmask_b32_e64 v93, v227, v93, s[38:39]
	v_max3_f32 v60, v60, v90, v91
	v_cndmask_b32_e64 v94, v227, v94, s[4:5]
	v_cndmask_b32_e64 v95, v227, v95, s[6:7]
	v_max3_f32 v60, v60, v92, v93
	v_cndmask_b32_e64 v96, v96, v227, s[16:17]
	v_cndmask_b32_e64 v97, v97, v227, s[18:19]
	v_max3_f32 v60, v60, v94, v95
	v_cndmask_b32_e64 v98, v98, v227, s[20:21]
	v_cndmask_b32_e64 v99, v99, v227, s[22:23]
	v_max3_f32 v60, v60, v96, v97
	v_cndmask_b32_e64 v4, v4, v227, s[52:53]
	v_cndmask_b32_e64 v5, v5, v227, s[10:11]
	v_max3_f32 v60, v60, v98, v99
	v_cndmask_b32_e64 v6, v6, v227, s[42:43]
	v_cndmask_b32_e64 v7, v7, v227, s[24:25]
	v_max3_f32 v60, v60, v4, v5
	v_max3_f32 v60, v60, v6, v7
	ds_bpermute_b32 v61, v80, v60
	s_movk_i32 s47, 0x110
	v_mul_lo_u32 v3, v3, s47
	v_add_u32_e32 v3, 0, v3
	s_mov_b32 s47, 1
	s_waitcnt lgkmcnt(0)
	v_max_f32_e32 v61, v61, v61
	v_max_f32_e32 v60, v60, v61
	ds_bpermute_b32 v61, v81, v60
	s_waitcnt lgkmcnt(0)
	v_max_f32_e32 v61, v61, v61
	v_max_f32_e32 v100, v60, v61
	v_max_f32_e32 v12, v12, v100
	v_sub_f32_e32 v58, v58, v12
	v_sub_f32_e32 v109, v100, v12
	v_lshrrev_b32_e32 v12, 2, v15
	v_add_u32_e32 v12, v12, v136
	v_bitop3_b32 v61, v12, 32, 60 bitop3:0x6c
	v_and_b32_e32 v15, 60, v12
	v_add_u32_e32 v60, 16, v12
	v_add_u32_e32 v12, 48, v12
	v_lshl_add_u32 v64, v61, 2, v3
	v_and_b32_e32 v12, 60, v12
	ds_read_b128 v[64:67], v64
	v_lshl_add_u32 v14, v15, 2, v3
	v_and_b32_e32 v15, 60, v60
	ds_read_b128 v[60:63], v14
	v_lshl_add_u32 v14, v15, 2, v3
	v_lshl_add_u32 v3, v12, 2, v3
	ds_read_b128 v[70:73], v14
	ds_read_b128 v[102:105], v3
	v_sub_f32_e32 v3, v8, v100
	v_sub_f32_e32 v8, v9, v100
	v_sub_f32_e32 v117, v94, v100
	v_exp_f32_e32 v94, v3
	v_sub_f32_e32 v9, v10, v100
	v_sub_f32_e32 v118, v95, v100
	v_exp_f32_e32 v95, v8
	v_sub_f32_e32 v10, v11, v100
	v_sub_f32_e32 v119, v96, v100
	v_exp_f32_e32 v96, v9
	v_sub_f32_e32 v11, v13, v100
	v_sub_f32_e32 v15, v19, v100
	v_sub_f32_e32 v19, v23, v100
	v_sub_f32_e32 v23, v69, v100
	v_sub_f32_e32 v69, v84, v100
	v_sub_f32_e32 v120, v97, v100
	v_exp_f32_e32 v97, v10
	v_sub_f32_e32 v12, v16, v100
	v_sub_f32_e32 v113, v90, v100
	v_sub_f32_e32 v121, v98, v100
	v_exp_f32_e32 v98, v11
	v_exp_f32_e32 v90, v19
	v_exp_f32_e32 v19, v23
	v_exp_f32_e32 v23, v69
	v_add_f32_e32 v69, 0, v94
	v_sub_f32_e32 v13, v17, v100
	v_sub_f32_e32 v122, v99, v100
	v_exp_f32_e32 v99, v12
	v_add_f32_e32 v69, v95, v69
	v_sub_f32_e32 v14, v18, v100
	v_sub_f32_e32 v16, v20, v100
	v_sub_f32_e32 v17, v21, v100
	v_sub_f32_e32 v18, v22, v100
	v_sub_f32_e32 v20, v24, v100
	v_sub_f32_e32 v21, v25, v100
	v_sub_f32_e32 v22, v68, v100
	v_sub_f32_e32 v24, v83, v100
	v_sub_f32_e32 v25, v74, v100
	v_sub_f32_e32 v68, v75, v100
	v_sub_f32_e32 v74, v85, v100
	v_sub_f32_e32 v75, v86, v100
	v_sub_f32_e32 v83, v87, v100
	v_sub_f32_e32 v84, v88, v100
	v_sub_f32_e32 v112, v89, v100
	v_sub_f32_e32 v114, v91, v100
	v_sub_f32_e32 v115, v92, v100
	v_sub_f32_e32 v116, v93, v100
	v_sub_f32_e32 v123, v4, v100
	v_sub_f32_e32 v124, v5, v100
	v_sub_f32_e32 v125, v6, v100
	v_sub_f32_e32 v126, v7, v100
	v_exp_f32_e32 v100, v13
	v_add_f32_e32 v69, v96, v69
	v_exp_f32_e32 v101, v14
	v_add_f32_e32 v69, v97, v69
	v_exp_f32_e32 v86, v15
	v_add_f32_e32 v69, v98, v69
	v_exp_f32_e32 v88, v16
	v_exp_f32_e32 v85, v83
	v_add_f32_e32 v83, v99, v69
	v_exp_f32_e32 v87, v17
	v_add_f32_e32 v83, v100, v83
	v_exp_f32_e32 v89, v18
	v_add_f32_e32 v83, v101, v83
	v_add_f32_e32 v83, v86, v83
	v_exp_f32_e32 v91, v20
	v_add_f32_e32 v83, v88, v83
	v_exp_f32_e32 v92, v21
	v_add_f32_e32 v83, v87, v83
	v_exp_f32_e32 v93, v22
	v_add_f32_e32 v83, v89, v83
	v_add_f32_e32 v83, v90, v83
	v_exp_f32_e32 v21, v24
	v_add_f32_e32 v83, v91, v83
	v_exp_f32_e32 v20, v25
	v_add_f32_e32 v83, v92, v83
	v_exp_f32_e32 v22, v68
	v_add_f32_e32 v83, v93, v83
	v_add_f32_e32 v83, v19, v83
	v_exp_f32_e32 v24, v74
	v_add_f32_e32 v83, v21, v83
	v_exp_f32_e32 v25, v75
	v_add_f32_e32 v83, v20, v83
	v_add_f32_e32 v83, v22, v83
	v_exp_f32_e32 v6, v84
	v_add_f32_e32 v83, v23, v83
	v_exp_f32_e32 v8, v112
	v_add_f32_e32 v83, v24, v83
	v_exp_f32_e32 v7, v113
	v_add_f32_e32 v83, v25, v83
	v_exp_f32_e32 v9, v114
	v_add_f32_e32 v83, v85, v83
	v_exp_f32_e32 v15, v115
	v_add_f32_e32 v83, v6, v83
	v_exp_f32_e32 v16, v116
	v_add_f32_e32 v83, v8, v83
	v_exp_f32_e32 v17, v117
	v_add_f32_e32 v83, v7, v83
	v_exp_f32_e32 v18, v118
	v_add_f32_e32 v83, v9, v83
	v_exp_f32_e32 v3, v119
	v_add_f32_e32 v83, v15, v83
	v_exp_f32_e32 v5, v120
	v_add_f32_e32 v83, v16, v83
	v_exp_f32_e32 v4, v121
	v_add_f32_e32 v83, v17, v83
	v_exp_f32_e32 v10, v122
	v_add_f32_e32 v83, v18, v83
	v_exp_f32_e32 v11, v123
	v_add_f32_e32 v83, v3, v83
	v_exp_f32_e32 v12, v124
	v_add_f32_e32 v83, v5, v83
	v_exp_f32_e32 v13, v125
	v_add_f32_e32 v83, v4, v83
	v_exp_f32_e32 v14, v126
	v_add_f32_e32 v83, v10, v83
	v_add_f32_e32 v83, v11, v83
	v_add_f32_e32 v83, v12, v83
	v_add_f32_e32 v83, v13, v83
	v_add_f32_e32 v83, v14, v83
	ds_bpermute_b32 v84, v80, v83
	v_cmp_gt_f32_e32 vcc, s48, v58
	v_cvt_pk_bf16_f32 v94, v94, v95
	v_cvt_pk_bf16_f32 v95, v96, v97
	v_cvt_pk_bf16_f32 v96, v98, v99
	s_waitcnt lgkmcnt(0)
	v_add_f32_e32 v83, v83, v84
	ds_bpermute_b32 v84, v81, v83
	v_cndmask_b32_e32 v107, 0, v225, vcc
	v_cndmask_b32_e32 v108, 0, v226, vcc
	v_cmp_gt_f32_e32 vcc, s48, v109
	v_add_f32_e32 v58, v58, v107
	v_exp_f32_e32 v58, v58
	v_cndmask_b32_e32 v110, 0, v225, vcc
	v_add_f32_e32 v68, v109, v110
	v_exp_f32_e32 v68, v68
	v_cndmask_b32_e32 v111, 0, v226, vcc
	v_ldexp_f32 v108, v58, v108
	v_pk_mul_f32 v[60:61], v[60:61], v[108:109] op_sel_hi:[1,0]
	v_ldexp_f32 v58, v68, v111
	v_pk_mul_f32 v[68:69], v[62:63], v[108:109] op_sel_hi:[1,0]
	v_pk_mul_f32 v[62:63], v[70:71], v[108:109] op_sel_hi:[1,0]
	v_pk_mul_f32 v[70:71], v[72:73], v[108:109] op_sel_hi:[1,0]
	v_pk_mul_f32 v[64:65], v[64:65], v[108:109] op_sel_hi:[1,0]
	v_pk_mul_f32 v[72:73], v[66:67], v[108:109] op_sel_hi:[1,0]
	v_pk_mul_f32 v[66:67], v[108:109], v[102:103] op_sel_hi:[0,1]
	v_pk_mul_f32 v[74:75], v[108:109], v[104:105] op_sel_hi:[0,1]
	v_mov_b32_e32 v109, v58
	s_waitcnt lgkmcnt(0)
	v_add_f32_e32 v107, v83, v84
	v_pk_mul_f32 v[102:103], v[106:107], v[108:109]
	v_add_u32_e32 v107, v78, v2
	v_add_f32_e32 v83, v102, v103
	v_div_scale_f32 v84, vcc, v83, v83, 1.0
	v_rcp_f32_e32 v102, v84
	v_ashrrev_i32_e32 v108, 5, v107
	v_ashrrev_i32_e32 v109, 31, v108
	v_lshlrev_b64 v[108:109], 12, v[108:109]
	v_fma_f32 v103, -v84, v102, 1.0
	v_fmac_f32_e32 v102, v103, v102
	v_div_scale_f32 v103, vcc, 1.0, v83, 1.0
	v_mul_f32_e32 v104, v103, v102
	v_fma_f32 v105, -v84, v104, v103
	v_fmac_f32_e32 v104, v105, v102
	v_fma_f32 v84, -v84, v104, v103
	v_div_fmas_f32 v84, v84, v102, v104
	v_or_b32_e32 v102, v2, v59
	v_add_u32_e32 v103, v76, v2
	v_add_u32_e32 v105, v77, v2
	v_ashrrev_i32_e32 v102, 5, v102
	v_ashrrev_i32_e32 v104, 5, v103
	v_ashrrev_i32_e32 v106, 5, v105
	v_ashrrev_i32_e32 v103, 31, v102
	v_ashrrev_i32_e32 v105, 31, v104
	v_ashrrev_i32_e32 v107, 31, v106
	v_lshlrev_b64 v[102:103], 12, v[102:103]
	v_lshlrev_b64 v[104:105], 12, v[104:105]
	v_lshlrev_b64 v[106:107], 12, v[106:107]
	v_lshl_add_u64 v[112:113], v[44:45], 0, v[102:103]
	v_lshl_add_u64 v[122:123], v[46:47], 0, v[104:105]
	v_lshl_add_u64 v[124:125], v[48:49], 0, v[106:107]
	v_lshl_add_u64 v[126:127], v[50:51], 0, v[108:109]
	v_or_b32_e32 v2, v2, v79
	v_ashrrev_i32_e32 v110, 5, v2
	v_ashrrev_i32_e32 v111, 31, v110
	v_lshlrev_b64 v[110:111], 12, v[110:111]
	v_lshl_add_u64 v[128:129], v[52:53], 0, v[110:111]
	global_load_dwordx4 v[102:105], v[112:113], off
	global_load_dwordx4 v[106:109], v[112:113], off offset:1024
	global_load_dwordx4 v[130:133], v[112:113], off offset:2048
	global_load_dwordx4 v[138:141], v[112:113], off offset:3072
	global_load_dwordx4 v[148:151], v[122:123], off
	global_load_dwordx4 v[152:155], v[122:123], off offset:1024
	global_load_dwordx4 v[156:159], v[122:123], off offset:2048
	global_load_dwordx4 v[160:163], v[122:123], off offset:3072
	global_load_dwordx4 v[164:167], v[124:125], off
	global_load_dwordx4 v[168:171], v[124:125], off offset:1024
	global_load_dwordx4 v[172:175], v[124:125], off offset:2048
	global_load_dwordx4 v[176:179], v[124:125], off offset:3072
	global_load_dwordx4 v[180:183], v[126:127], off
	global_load_dwordx4 v[184:187], v[126:127], off offset:1024
	global_load_dwordx4 v[188:191], v[126:127], off offset:2048
	global_load_dwordx4 v[192:195], v[126:127], off offset:3072
	global_load_dwordx4 v[196:199], v[128:129], off
	global_load_dwordx4 v[200:203], v[128:129], off offset:1024
	global_load_dwordx4 v[204:207], v[128:129], off offset:2048
	global_load_dwordx4 v[208:211], v[128:129], off offset:3072
	v_cvt_pk_bf16_f32 v97, v100, v101
	v_cvt_pk_bf16_f32 v86, v86, v88
	v_cvt_pk_bf16_f32 v87, v87, v89
	v_cvt_pk_bf16_f32 v88, v90, v91
	v_cvt_pk_bf16_f32 v89, v92, v93
	v_cvt_pk_bf16_f32 v6, v6, v8
	v_cvt_pk_bf16_f32 v7, v7, v9
	v_cvt_pk_bf16_f32 v8, v15, v16
	v_cvt_pk_bf16_f32 v9, v17, v18
	v_cvt_pk_bf16_f32 v2, v3, v5
	v_cvt_pk_bf16_f32 v3, v4, v10
	v_cvt_pk_bf16_f32 v4, v11, v12
	v_cvt_pk_bf16_f32 v5, v13, v14
	v_cvt_pk_bf16_f32 v118, v19, v21
	v_cvt_pk_bf16_f32 v119, v20, v22
	v_cvt_pk_bf16_f32 v120, v23, v24
	v_cvt_pk_bf16_f32 v121, v25, v85
	s_mov_b64 vcc, 0x15000600
	v_lshl_add_u64 v[56:57], v[56:57], 0, vcc
	s_andn2_b64 vcc, exec, s[2:3]
	s_mov_b64 s[2:3], 0
	s_waitcnt vmcnt(16)
	v_mfma_f32_16x16x32_bf16 v[102:105], v[102:105], v[94:97], 0
	v_mfma_f32_16x16x32_bf16 v[106:109], v[106:109], v[94:97], 0
	v_mfma_f32_16x16x32_bf16 v[130:133], v[130:133], v[94:97], 0
	v_mfma_f32_16x16x32_bf16 v[138:141], v[138:141], v[94:97], 0
	s_waitcnt vmcnt(12)
	v_mfma_f32_16x16x32_bf16 v[102:105], v[148:151], v[86:89], v[102:105]
	v_mfma_f32_16x16x32_bf16 v[106:109], v[152:155], v[86:89], v[106:109]
	v_mfma_f32_16x16x32_bf16 v[130:133], v[156:159], v[86:89], v[130:133]
	v_mfma_f32_16x16x32_bf16 v[138:141], v[160:163], v[86:89], v[138:141]
	s_waitcnt vmcnt(8)
	v_mfma_f32_16x16x32_bf16 v[102:105], v[164:167], v[118:121], v[102:105]
	v_mfma_f32_16x16x32_bf16 v[106:109], v[168:171], v[118:121], v[106:109]
	v_mfma_f32_16x16x32_bf16 v[130:133], v[172:175], v[118:121], v[130:133]
	v_mfma_f32_16x16x32_bf16 v[138:141], v[176:179], v[118:121], v[138:141]
	s_waitcnt vmcnt(4)
	v_mfma_f32_16x16x32_bf16 v[102:105], v[180:183], v[6:9], v[102:105]
	v_mfma_f32_16x16x32_bf16 v[106:109], v[184:187], v[6:9], v[106:109]
	v_mfma_f32_16x16x32_bf16 v[130:133], v[188:191], v[6:9], v[130:133]
	v_mfma_f32_16x16x32_bf16 v[138:141], v[192:195], v[6:9], v[138:141]
	s_waitcnt vmcnt(0)
	v_mfma_f32_16x16x32_bf16 v[10:13], v[196:199], v[2:5], v[102:105]
	v_mfma_f32_16x16x32_bf16 v[14:17], v[200:203], v[2:5], v[106:109]
	v_mfma_f32_16x16x32_bf16 v[18:21], v[204:207], v[2:5], v[130:133]
	v_mfma_f32_16x16x32_bf16 v[86:89], v[208:211], v[2:5], v[138:141]
	s_nop 7
	s_nop 3
	v_pk_fma_f32 v[12:13], v[12:13], v[58:59], v[68:69] op_sel_hi:[1,0,1]
	v_pk_fma_f32 v[14:15], v[14:15], v[58:59], v[62:63] op_sel_hi:[1,0,1]
	v_fma_f32 v22, v10, v58, v60
	v_fma_f32 v23, v11, v58, v61
	s_nop 0
	v_pk_fma_f32 v[8:9], v[16:17], v[58:59], v[70:71] op_sel_hi:[1,0,1]
	v_pk_fma_f32 v[4:5], v[20:21], v[58:59], v[72:73] op_sel_hi:[1,0,1]
	v_pk_fma_f32 v[10:11], v[18:19], v[58:59], v[64:65] op_sel_hi:[1,0,1]
	s_nop 1
	v_pk_fma_f32 v[2:3], v[88:89], v[58:59], v[74:75] op_sel_hi:[1,0,1]
	v_pk_fma_f32 v[6:7], v[86:87], v[58:59], v[66:67] op_sel_hi:[1,0,1]
	v_div_fixup_f32 v16, v84, v83, 1.0
	v_mul_f32_e32 v17, v16, v22
	v_mul_f32_e32 v18, v16, v23
	v_mul_f32_e32 v12, v16, v12
	v_mul_f32_e32 v13, v16, v13
	v_mul_f32_e32 v14, v16, v14
	v_mul_f32_e32 v15, v16, v15
	v_mul_f32_e32 v8, v16, v8
	v_mul_f32_e32 v9, v16, v9
	v_mul_f32_e32 v10, v16, v10
	v_mul_f32_e32 v11, v16, v11
	v_mul_f32_e32 v19, v16, v4
	v_mul_f32_e32 v20, v16, v5
	v_mul_f32_e32 v21, v16, v6
	v_mul_f32_e32 v22, v16, v7
	v_mul_f32_e32 v23, v16, v2
	v_mul_f32_e32 v16, v16, v3
	v_cvt_pk_bf16_f32 v2, v17, v18
	v_cvt_pk_bf16_f32 v3, v12, v13
	v_cvt_pk_bf16_f32 v4, v14, v15
	v_cvt_pk_bf16_f32 v5, v8, v9
	v_cvt_pk_bf16_f32 v6, v10, v11
	v_cvt_pk_bf16_f32 v7, v19, v20
	v_cvt_pk_bf16_f32 v8, v21, v22
	v_cvt_pk_bf16_f32 v9, v23, v16
	flat_store_dwordx2 v[54:55], v[2:3] offset:1536
	flat_store_dwordx2 v[56:57], v[4:5] offset:32
	flat_store_dwordx2 v[56:57], v[6:7] offset:64
	flat_store_dwordx2 v[56:57], v[8:9] offset:96
	s_cbranch_vccz .LBB0_178
	v_readlane_b32 s82, v253, 29
	v_readlane_b32 s48, v255, 57
	v_readlane_b32 s66, v255, 59
	v_readlane_b32 s68, v255, 61
	v_readlane_b32 s70, v255, 63
	v_readlane_b32 s74, v254, 1
	v_readlane_b32 s76, v254, 3
	v_readlane_b32 s78, v254, 5
	v_readlane_b32 s80, v254, 7
	s_mov_b32 s92, 0x2600000
	s_movk_i32 s73, 0x110
	s_mov_b32 s36, 0xf800000
	s_mov_b64 s[34:35], 0xc000
	v_readlane_b32 s83, v253, 30
	s_mov_b32 s97, 0xff800000
	v_readlane_b32 s49, v255, 58
	v_readlane_b32 s67, v255, 60
	v_readlane_b32 s69, v255, 62
	v_readlane_b32 s71, v254, 0
	v_readlane_b32 s75, v254, 2
	v_readlane_b32 s77, v254, 4
	v_readlane_b32 s79, v254, 6
	v_readlane_b32 s81, v254, 8
	v_readlane_b32 s41, v253, 32
	s_branch .LBB0_133
